# v32: v31 + P1 odd-XCD workgroups start their tile loop ~8 us late (two s_sleep 127): the two grid halves no longer burst their epilogue stores at the same time
# speedup vs baseline: 1.0291x; 1.0050x over previous
; #define PG8_STAGE(bufoff, gbase, voff) do { _Pragma("unroll") for (int _i = 0; _i < 2; ++_i) \
;         __builtin_amdgcn_global_load_lds((const unsigned*)((const char*)(gbase) + (voff)[_i]), (LAS unsigned*)(lds + (bufoff) + ldsw + _i * 8192), 16, 0, 0); } while (0)
; #define PG8_BAR __builtin_amdgcn_s_barrier()
; template <class Epi, int AC0, int BC0, int NT0, int AC1, int BC1, int NT1>
; __device__ __forceinline__ void gemm_phase(LAS unsigned char* lds, const Gemm g, const StaticOrder& S, const Epi& E, int tid) {
;     const int wid = __builtin_amdgcn_readfirstlane(tid >> 6), lane = tid & 63, wr = wid >> 2, wc = wid & 3, fr = lane & 15, fq = lane >> 4;
;     unsigned voffA[2], voffB[2];
; #pragma unroll
;     for (int i = 0; i < 2; ++i) { int R, C; stage_rc(tid * 16 + i * 8192, R, C); const int Rb = (R & ~31) + perm32(R & 31);
;         voffA[i] = (unsigned)(R * g.lda + C) * 2u; voffB[i] = (unsigned)(Rb * g.ldb + C) * 2u; }
;     const size_t kstep = (size_t)(BK * 2);
;     const size_t hstepA = (size_t)HALF * g.lda * 2, hstepB = (size_t)HALF * g.ldb * 2;
;     const unsigned ldsw = (unsigned)wid * 1024u;
;     const int aoff = lds_byte(wr * 64 + fr, fq * 8), boff = lds_byte(wc * 32 + fr, fq * 8);
;     ...
;     Unit cur, nxt; int ui = 0;
;     if (!S.next(0, cur)) return;
;     f32x4 acc[2][2][4][2];
; #pragma unroll
;     for (int a = 0; a < 2; ++a)
; #pragma unroll
;         for (int b = 0; b < 2; ++b)
; #pragma unroll
;             for (int m = 0; m < 4; ++m)
; #pragma unroll
;                 for (int n = 0; n < 2; ++n) acc[a][b][m][n] = (f32x4){0.f, 0.f, 0.f, 0.f};
;     bf16x8 At[4][2], B0[2][2], B1[2][2];
;     const char* cA = PG8_APTR(cur); const char* cB = PG8_BPTR(cur);
;     PG8_STAGE(PG8_SB(0, 0), cB, voffB); PG8_STAGE(PG8_SB(0, 1), cB + hstepB, voffB); PG8_STAGE(PG8_SA(0, 0), cA, voffA); PG8_STAGE(PG8_SA(0, 1), cA + hstepA, voffA);
;     if (wr == 1) PG8_BAR;
.LBB0_111:
	s_ashr_i32 s3, s93, 31
	v_writelane_b32 v254, s3, 9
	s_ashr_i32 s95, s94, 31
	s_bitcmp1_b32 s94, 0
	s_cbranch_scc0 .Lp1lag_skip
	s_sleep 127
	s_sleep 127
.Lp1lag_skip:
	s_add_u32 s82, s62, 0x5a00000
	v_writelane_b32 v254, s94, 10
	s_addc_u32 s83, s63, 0
	s_andn2_b64 vcc, exec, s[0:1]
	v_writelane_b32 v254, s95, 11
	v_writelane_b32 v254, s93, 12
	s_cbranch_vccnz .LBB0_385
	v_ashrrev_i32_e32 v2, 31, v10
	v_lshrrev_b32_e32 v2, 26, v2
	v_add_u32_e32 v2, v10, v2
	v_ashrrev_i32_e32 v11, 6, v2
	v_bfe_i32 v2, v10, 27, 1
	v_lshlrev_b32_e32 v1, 4, v10
	v_lshrrev_b32_e32 v2, 22, v2
	v_add_u32_e32 v2, v1, v2
	v_and_b32_e32 v2, 0xfffffc00, v2
	v_sub_u32_e32 v2, v1, v2
	v_lshrrev_b32_e32 v3, 4, v2
	v_bitop3_b32 v3, v3, v2, 32 bitop3:0x6c
	v_ashrrev_i32_e32 v2, 31, v2
	v_lshrrev_b32_e32 v2, 26, v2
	v_add_u32_e32 v2, v3, v2
	v_ashrrev_i32_e32 v12, 6, v2
	v_lshlrev_b32_e32 v4, 3, v11
	v_mul_i32_i24_e32 v5, 64, v12
	v_and_b32_e32 v4, -16, v4
	v_sub_u32_e32 v3, v3, v5
	v_mov_b32_e32 v5, 1
	v_add_u32_e32 v2, v12, v4
	v_lshlrev_b32_e32 v4, 5, v11
	v_ashrrev_i16_sdwa v3, v5, sext(v3) dst_sel:DWORD dst_unused:UNUSED_PAD src0_sel:DWORD src1_sel:BYTE_0
	v_and_b32_e32 v4, 32, v4
	v_bfe_i32 v13, v3, 0, 16
	v_and_b32_e32 v7, 3, v12
	s_mov_b32 s0, 0x1fffe0
	v_add_lshl_u32 v4, v4, v13, 1
	v_add_u32_e32 v1, 0x2000, v1
	v_lshlrev_b32_e32 v3, 1, v2
	v_lshrrev_b32_e32 v6, 2, v2
	v_and_or_b32 v7, v2, s0, v7
	v_lshl_add_u32 v164, v2, 11, v4
	v_ashrrev_i32_e32 v2, 31, v1
	v_lshrrev_b32_e32 v2, 22, v2
	v_add_u32_e32 v2, v1, v2
	v_ashrrev_i32_e32 v14, 10, v2
	v_mul_i32_i24_e32 v2, 0x400, v14
	v_sub_u32_e32 v1, v1, v2
	v_and_b32_e32 v3, 24, v3
	v_and_b32_e32 v6, 4, v6
	v_lshrrev_b32_e32 v2, 4, v1
	v_or3_b32 v3, v7, v6, v3
	v_bitop3_b32 v1, v2, v1, 32 bitop3:0x6c
	v_lshl_add_u32 v166, v3, 11, v4
	v_ashrrev_i32_e32 v3, 31, v1
	v_lshrrev_b32_e32 v3, 26, v3
	v_add_u32_e32 v3, v1, v3
	v_lshlrev_b32_e32 v2, 3, v14
	v_ashrrev_i32_e32 v15, 6, v3
	v_and_b32_e32 v3, 0xc0, v3
	v_and_b32_e32 v2, -16, v2
	v_sub_u32_e32 v1, v1, v3
	v_writelane_b32 v254, s33, 13
	s_ashr_i32 s3, s2, 6
	v_add_u32_e32 v2, v15, v2
	v_ashrrev_i16_sdwa v1, v5, sext(v1) dst_sel:DWORD dst_unused:UNUSED_PAD src0_sel:DWORD src1_sel:BYTE_0
	v_and_b32_e32 v5, 3, v15
	s_ashr_i32 s11, s10, 31
	s_ashr_i32 s9, s8, 31
	v_and_or_b32 v5, v2, s0, v5
	s_ashr_i32 s4, s2, 8
	s_lshl_b32 s47, s3, 10
	s_lshl_b64 s[0:1], s[10:11], 19
	s_lshl_b64 s[6:7], s[8:9], 19
	v_readlane_b32 s12, v254, 4
	v_readlane_b32 s13, v254, 5
	s_add_u32 s6, s12, s6
	v_lshlrev_b32_e32 v4, 5, v14
	v_bfe_i32 v16, v1, 0, 16
	v_lshlrev_b32_e32 v1, 1, v2
	v_lshrrev_b32_e32 v3, 2, v2
	s_addc_u32 s7, s13, s7
	s_add_i32 s95, s47, 0
	v_and_b32_e32 v4, 32, v4
	v_and_b32_e32 v1, 24, v1
	v_and_b32_e32 v3, 4, v3
	s_add_i32 m0, s95, 0x10000
	v_or3_b32 v1, v5, v3, v1
	v_add_lshl_u32 v3, v4, v16, 1
	global_load_lds_dwordx4 v166, s[6:7]
	s_add_i32 m0, s95, 0x12000
	v_lshl_add_u32 v170, v1, 11, v3
	s_add_u32 s12, s6, 0x40000
	global_load_lds_dwordx4 v170, s[6:7]
	s_addc_u32 s13, s7, 0
	s_add_i32 m0, s95, 0x14000
	v_lshl_add_u32 v168, v2, 11, v3
	global_load_lds_dwordx4 v166, s[12:13]
	s_add_i32 m0, s95, 0x16000
	s_add_u32 s0, s80, s0
	s_addc_u32 s1, s81, s1
	s_add_i32 s96, s95, 0x2000
	global_load_lds_dwordx4 v170, s[12:13]
	s_mov_b32 m0, s95
	s_add_u32 s12, s0, 0x40000
	global_load_lds_dwordx4 v164, s[0:1]
	s_mov_b32 m0, s96
	s_addc_u32 s13, s1, 0
	s_add_i32 s97, s95, 0x4000
	global_load_lds_dwordx4 v168, s[0:1]
	s_mov_b32 m0, s97
	s_add_i32 s93, s95, 0x6000
	global_load_lds_dwordx4 v164, s[12:13]
	s_mov_b32 m0, s93
	v_mov_b32_e32 v173, 0
	global_load_lds_dwordx4 v168, s[12:13]
	s_cmp_eq_u32 s4, 1
	v_mov_b32_e32 v167, v173
	v_mov_b32_e32 v171, v173
	v_mov_b32_e32 v165, v173
	v_mov_b32_e32 v169, v173
	s_cselect_b64 s[12:13], -1, 0
	s_mov_b32 s17, 0
	v_lshl_add_u64 v[6:7], s[6:7], 0, v[166:167]
	v_lshl_add_u64 v[4:5], s[6:7], 0, v[170:171]
	v_lshl_add_u64 v[2:3], s[0:1], 0, v[164:165]
	v_writelane_b32 v254, s12, 15
	s_cmp_lg_u32 s4, 1
	v_lshl_add_u64 v[8:9], s[0:1], 0, v[168:169]
	v_writelane_b32 v254, s13, 16
	s_cbranch_scc1 .LBB0_114
	s_barrier
